# attention loops: second staging waits only for the loads it writes (vmcnt(0) only when no further tile was requested)
# speedup vs baseline: 1.0150x; 1.0077x over previous
.LBB0_1091:
	ds_read_b64_tr_b16 v[160:161], v174 offset:0
	ds_read_b64_tr_b16 v[162:163], v174 offset:0x800
	ds_read_b64_tr_b16 v[196:197], v174 offset:0x1000
	ds_read_b64_tr_b16 v[198:199], v174 offset:0x1800
	ds_read_b64_tr_b16 v[200:201], v174 offset:0x2000
	ds_read_b64_tr_b16 v[202:203], v174 offset:0x2800
	ds_read_b64_tr_b16 v[204:205], v174 offset:0x3000
	ds_read_b64_tr_b16 v[206:207], v174 offset:0x3800
	s_waitcnt lgkmcnt(0)
	s_nop 0
	v_mfma_f32_32x32x16_bf16 v[0:15], v[136:139], v[160:163], v[0:15]
	ds_read_b64_tr_b16 v[160:161], v174 offset:0x200
	ds_read_b64_tr_b16 v[162:163], v174 offset:0xa00
	v_mfma_f32_32x32x16_bf16 v[0:15], v[140:143], v[196:199], v[0:15]
	ds_read_b64_tr_b16 v[196:197], v174 offset:0x1200
	ds_read_b64_tr_b16 v[198:199], v174 offset:0x1a00
	v_mfma_f32_32x32x16_bf16 v[0:15], v[144:147], v[200:203], v[0:15]
	ds_read_b64_tr_b16 v[200:201], v174 offset:0x2200
	ds_read_b64_tr_b16 v[202:203], v174 offset:0x2a00
	v_mfma_f32_32x32x16_bf16 v[0:15], v[148:151], v[204:207], v[0:15]
	ds_read_b64_tr_b16 v[204:205], v174 offset:0x3200
	ds_read_b64_tr_b16 v[206:207], v174 offset:0x3a00
	s_waitcnt lgkmcnt(0)
	v_mfma_f32_32x32x16_bf16 v[48:63], v[136:139], v[160:163], v[48:63]
	ds_read_b64_tr_b16 v[160:161], v174 offset:0x400
	ds_read_b64_tr_b16 v[162:163], v174 offset:0xc00
	v_mfma_f32_32x32x16_bf16 v[48:63], v[140:143], v[196:199], v[48:63]
	ds_read_b64_tr_b16 v[196:197], v174 offset:0x1400
	ds_read_b64_tr_b16 v[198:199], v174 offset:0x1c00
	v_mfma_f32_32x32x16_bf16 v[48:63], v[144:147], v[200:203], v[48:63]
	ds_read_b64_tr_b16 v[200:201], v174 offset:0x2400
	ds_read_b64_tr_b16 v[202:203], v174 offset:0x2c00
	v_mfma_f32_32x32x16_bf16 v[48:63], v[148:151], v[204:207], v[48:63]
	ds_read_b64_tr_b16 v[204:205], v174 offset:0x3400
	ds_read_b64_tr_b16 v[206:207], v174 offset:0x3c00
	s_waitcnt lgkmcnt(0)
	v_mfma_f32_32x32x16_bf16 v[32:47], v[136:139], v[160:163], v[32:47]
	ds_read_b64_tr_b16 v[160:161], v174 offset:0x600
	ds_read_b64_tr_b16 v[162:163], v174 offset:0xe00
	v_mfma_f32_32x32x16_bf16 v[32:47], v[140:143], v[196:199], v[32:47]
	ds_read_b64_tr_b16 v[196:197], v174 offset:0x1600
	ds_read_b64_tr_b16 v[198:199], v174 offset:0x1e00
	v_mfma_f32_32x32x16_bf16 v[32:47], v[144:147], v[200:203], v[32:47]
	ds_read_b64_tr_b16 v[200:201], v174 offset:0x2600
	ds_read_b64_tr_b16 v[202:203], v174 offset:0x2e00
	v_mfma_f32_32x32x16_bf16 v[32:47], v[148:151], v[204:207], v[32:47]
	ds_read_b64_tr_b16 v[204:205], v174 offset:0x3600
	ds_read_b64_tr_b16 v[206:207], v174 offset:0x3e00
	s_waitcnt lgkmcnt(0)
	v_mfma_f32_32x32x16_bf16 v[16:31], v[136:139], v[160:163], v[16:31]
	v_max_f32_e32 v136, v81, v81
	v_max_f32_e32 v137, v80, v80
	v_max_f32_e32 v136, v137, v136
	v_max3_f32 v136, v136, v82, v83
	v_max3_f32 v136, v136, v84, v85
	v_max3_f32 v136, v136, v86, v87
	v_max3_f32 v136, v136, v88, v89
	v_max3_f32 v136, v136, v90, v91
	v_max3_f32 v136, v136, v92, v93
	v_mfma_f32_32x32x16_bf16 v[16:31], v[140:143], v[196:199], v[16:31]
	v_max3_f32 v136, v136, v94, v95
	v_max3_f32 v136, v136, v64, v65
	v_max3_f32 v136, v136, v66, v67
	v_max3_f32 v136, v136, v68, v69
	v_max3_f32 v136, v136, v70, v71
	v_max3_f32 v136, v136, v72, v73
	v_max3_f32 v136, v136, v74, v75
	v_max3_f32 v136, v136, v76, v77
	v_mfma_f32_32x32x16_bf16 v[16:31], v[144:147], v[200:203], v[16:31]
	v_max3_f32 v136, v136, v78, v79
	v_mov_b32_e32 v137, v136
	s_nop 1
	v_permlane32_swap_b32_e32 v136, v137
	v_max_f32_e32 v137, v137, v137
	v_max_f32_e32 v136, v136, v136
	v_max_f32_e32 v136, v136, v137
	v_sub_f32_e32 v137, v136, v193
	v_cmp_ge_f32_e32 vcc, s38, v137
	v_max_f32_e32 v137, v193, v193
	v_max_f32_e32 v136, v137, v136
	v_mfma_f32_32x32x16_bf16 v[16:31], v[148:151], v[204:207], v[16:31]
	v_sub_f32_e32 v137, v193, v136
	v_mul_f32_e32 v137, 0x3e38aa3b, v137
	v_exp_f32_e32 v137, v137
	s_cmp_eq_u64 vcc, exec
	s_cselect_b64 s[4:5], -1, 0
	s_barrier
	s_waitcnt vmcnt(3)
	v_cndmask_b32_e64 v141, v137, 1.0, s[4:5]
	v_cmp_gt_f32_e32 vcc, 1.0, v141
	s_cmp_lg_u64 s[8:9], 0
	s_cbranch_scc0 .Lsw_da
	s_waitcnt vmcnt(0)
.Lsw_da:
	ds_write_b128 v179, v[124:127] offset:16384
	ds_write_b128 v180, v[128:131] offset:16384
	ds_write_b128 v186, v[132:135] offset:40960
	s_cbranch_vccz .LBB0_1095
	s_and_saveexec_b64 s[10:11], s[6:7]
	ds_write_b32 v155, v141 offset:49280
	s_or_b64 exec, exec, s[10:11]
	s_waitcnt lgkmcnt(0)
	v_add_u32_e32 v137, v153, v178
	ds_read_b128 v[124:127], v137 offset:49376
	ds_read_b128 v[128:131], v137 offset:49344
	ds_read_b128 v[132:135], v137 offset:49312
	ds_read_b128 v[142:145], v137 offset:49280
	s_waitcnt lgkmcnt(3)
	v_pk_mul_f32 v[12:13], v[12:13], v[124:125]
	s_waitcnt lgkmcnt(2)
	v_pk_mul_f32 v[8:9], v[8:9], v[128:129]
	s_waitcnt lgkmcnt(1)
	v_pk_mul_f32 v[4:5], v[4:5], v[132:133]
	v_pk_mul_f32 v[14:15], v[14:15], v[126:127]
	v_pk_mul_f32 v[10:11], v[10:11], v[130:131]
	v_pk_mul_f32 v[6:7], v[6:7], v[134:135]
	s_waitcnt lgkmcnt(0)
	v_pk_mul_f32 v[2:3], v[2:3], v[144:145]
	v_pk_mul_f32 v[0:1], v[0:1], v[142:143]
	v_pk_mul_f32 v[60:61], v[60:61], v[124:125]
	v_pk_mul_f32 v[56:57], v[56:57], v[128:129]
	v_pk_mul_f32 v[52:53], v[52:53], v[132:133]
	v_pk_mul_f32 v[62:63], v[62:63], v[126:127]
	v_pk_mul_f32 v[58:59], v[58:59], v[130:131]
	v_pk_mul_f32 v[54:55], v[54:55], v[134:135]
	v_pk_mul_f32 v[50:51], v[50:51], v[144:145]
	v_pk_mul_f32 v[48:49], v[48:49], v[142:143]
	v_pk_mul_f32 v[44:45], v[44:45], v[124:125]
	v_pk_mul_f32 v[40:41], v[40:41], v[128:129]
	v_pk_mul_f32 v[36:37], v[36:37], v[132:133]
	v_pk_mul_f32 v[46:47], v[46:47], v[126:127]
	v_pk_mul_f32 v[42:43], v[42:43], v[130:131]
	v_pk_mul_f32 v[38:39], v[38:39], v[134:135]
	v_pk_mul_f32 v[34:35], v[34:35], v[144:145]
	v_pk_mul_f32 v[32:33], v[32:33], v[142:143]
	v_pk_mul_f32 v[28:29], v[28:29], v[124:125]
	v_pk_mul_f32 v[24:25], v[24:25], v[128:129]
	v_pk_mul_f32 v[20:21], v[20:21], v[132:133]
	v_pk_mul_f32 v[30:31], v[30:31], v[126:127]
	v_pk_mul_f32 v[26:27], v[26:27], v[130:131]
	v_pk_mul_f32 v[22:23], v[22:23], v[134:135]
	v_pk_mul_f32 v[18:19], v[18:19], v[144:145]
	v_pk_mul_f32 v[16:17], v[16:17], v[142:143]

.LBB0_1112:
	ds_read_b64_tr_b16 v[208:209], v187 offset:0
	ds_read_b64_tr_b16 v[210:211], v187 offset:0x800
	ds_read_b64_tr_b16 v[232:233], v187 offset:0x1000
	ds_read_b64_tr_b16 v[234:235], v187 offset:0x1800
	ds_read_b64_tr_b16 v[236:237], v187 offset:0x2000
	ds_read_b64_tr_b16 v[238:239], v187 offset:0x2800
	ds_read_b64_tr_b16 v[240:241], v187 offset:0x3000
	ds_read_b64_tr_b16 v[242:243], v187 offset:0x3800
	s_waitcnt lgkmcnt(0)
	s_nop 0
	v_mfma_f32_32x32x16_bf16 v[0:15], v[160:163], v[208:211], v[0:15]
	ds_read_b64_tr_b16 v[208:209], v187 offset:0x200
	ds_read_b64_tr_b16 v[210:211], v187 offset:0xa00
	v_mfma_f32_32x32x16_bf16 v[0:15], v[164:167], v[232:235], v[0:15]
	ds_read_b64_tr_b16 v[232:233], v187 offset:0x1200
	ds_read_b64_tr_b16 v[234:235], v187 offset:0x1a00
	v_mfma_f32_32x32x16_bf16 v[0:15], v[168:171], v[236:239], v[0:15]
	ds_read_b64_tr_b16 v[236:237], v187 offset:0x2200
	ds_read_b64_tr_b16 v[238:239], v187 offset:0x2a00
	v_mfma_f32_32x32x16_bf16 v[0:15], v[172:175], v[240:243], v[0:15]
	ds_read_b64_tr_b16 v[240:241], v187 offset:0x3200
	ds_read_b64_tr_b16 v[242:243], v187 offset:0x3a00
	s_waitcnt lgkmcnt(0)
	v_mfma_f32_32x32x16_bf16 v[48:63], v[160:163], v[208:211], v[48:63]
	ds_read_b64_tr_b16 v[208:209], v187 offset:0x400
	ds_read_b64_tr_b16 v[210:211], v187 offset:0xc00
	v_mfma_f32_32x32x16_bf16 v[48:63], v[164:167], v[232:235], v[48:63]
	ds_read_b64_tr_b16 v[232:233], v187 offset:0x1400
	ds_read_b64_tr_b16 v[234:235], v187 offset:0x1c00
	v_mfma_f32_32x32x16_bf16 v[48:63], v[168:171], v[236:239], v[48:63]
	ds_read_b64_tr_b16 v[236:237], v187 offset:0x2400
	ds_read_b64_tr_b16 v[238:239], v187 offset:0x2c00
	v_mfma_f32_32x32x16_bf16 v[48:63], v[172:175], v[240:243], v[48:63]
	ds_read_b64_tr_b16 v[240:241], v187 offset:0x3400
	ds_read_b64_tr_b16 v[242:243], v187 offset:0x3c00
	s_waitcnt lgkmcnt(0)
	v_mfma_f32_32x32x16_bf16 v[32:47], v[160:163], v[208:211], v[32:47]
	ds_read_b64_tr_b16 v[208:209], v187 offset:0x600
	ds_read_b64_tr_b16 v[210:211], v187 offset:0xe00
	v_mfma_f32_32x32x16_bf16 v[32:47], v[164:167], v[232:235], v[32:47]
	ds_read_b64_tr_b16 v[232:233], v187 offset:0x1600
	ds_read_b64_tr_b16 v[234:235], v187 offset:0x1e00
	v_mfma_f32_32x32x16_bf16 v[32:47], v[168:171], v[236:239], v[32:47]
	ds_read_b64_tr_b16 v[236:237], v187 offset:0x2600
	ds_read_b64_tr_b16 v[238:239], v187 offset:0x2e00
	v_mfma_f32_32x32x16_bf16 v[32:47], v[172:175], v[240:243], v[32:47]
	ds_read_b64_tr_b16 v[240:241], v187 offset:0x3600
	ds_read_b64_tr_b16 v[242:243], v187 offset:0x3e00
	s_waitcnt lgkmcnt(0)
	v_mfma_f32_32x32x16_bf16 v[16:31], v[160:163], v[208:211], v[16:31]
	v_max_f32_e32 v160, v81, v81
	v_max_f32_e32 v161, v80, v80
	v_max_f32_e32 v160, v161, v160
	v_max3_f32 v160, v160, v82, v83
	v_max3_f32 v160, v160, v84, v85
	v_max3_f32 v160, v160, v86, v87
	v_max3_f32 v160, v160, v88, v89
	v_max3_f32 v160, v160, v90, v91
	v_max3_f32 v160, v160, v92, v93
	v_mfma_f32_32x32x16_bf16 v[16:31], v[164:167], v[232:235], v[16:31]
	v_max3_f32 v160, v160, v94, v95
	v_max3_f32 v160, v160, v64, v65
	v_max3_f32 v160, v160, v66, v67
	v_max3_f32 v160, v160, v68, v69
	v_max3_f32 v160, v160, v70, v71
	v_max3_f32 v160, v160, v72, v73
	v_max3_f32 v160, v160, v74, v75
	v_max3_f32 v160, v160, v76, v77
	v_mfma_f32_32x32x16_bf16 v[16:31], v[168:171], v[236:239], v[16:31]
	v_max3_f32 v160, v160, v78, v79
	v_mov_b32_e32 v161, v160
	s_nop 1
	v_permlane32_swap_b32_e32 v160, v161
	v_max_f32_e32 v161, v161, v161
	v_max_f32_e32 v160, v160, v160
	v_max_f32_e32 v160, v160, v161
	v_sub_f32_e32 v161, v160, v205
	v_cmp_ge_f32_e32 vcc, s42, v161
	v_max_f32_e32 v161, v205, v205
	v_max_f32_e32 v161, v161, v160
	v_mfma_f32_32x32x16_bf16 v[16:31], v[172:175], v[240:243], v[16:31]
	v_sub_f32_e32 v160, v205, v161
	v_mul_f32_e32 v160, 0x3e0293ee, v160
	v_exp_f32_e32 v160, v160
	s_cmp_eq_u64 vcc, exec
	s_cselect_b64 s[4:5], -1, 0
	s_barrier
	s_waitcnt vmcnt(4)
	v_cndmask_b32_e64 v160, v160, 1.0, s[4:5]
	v_cmp_gt_f32_e32 vcc, 1.0, v160
	s_cmp_lg_u64 s[8:9], 0
	s_cbranch_scc0 .Lsw_gqa
	s_waitcnt vmcnt(0)
.Lsw_gqa:
	ds_write_b128 v192, v[144:147] offset:16384
	ds_write_b128 v193, v[156:159] offset:16384
	ds_write_b128 v190, v[148:151] offset:49152
	ds_write_b128 v191, v[152:155] offset:49152
	s_cbranch_vccz .LBB0_1116
	s_and_saveexec_b64 s[10:11], s[6:7]
	ds_write_b32 v179, v160 offset:128
	s_or_b64 exec, exec, s[10:11]
	s_waitcnt lgkmcnt(0)
	v_add_u32_e32 v156, v176, v178
	ds_read_b128 v[144:147], v156 offset:224
	ds_read_b128 v[148:151], v156 offset:192
	ds_read_b128 v[152:155], v156 offset:160
	ds_read_b128 v[156:159], v156 offset:128
	s_waitcnt lgkmcnt(3)
	v_pk_mul_f32 v[12:13], v[12:13], v[144:145]
	s_waitcnt lgkmcnt(2)
	v_pk_mul_f32 v[8:9], v[8:9], v[148:149]
	s_waitcnt lgkmcnt(1)
	v_pk_mul_f32 v[4:5], v[4:5], v[152:153]
	v_pk_mul_f32 v[14:15], v[14:15], v[146:147]
	v_pk_mul_f32 v[10:11], v[10:11], v[150:151]
	v_pk_mul_f32 v[6:7], v[6:7], v[154:155]
	s_waitcnt lgkmcnt(0)
	v_pk_mul_f32 v[2:3], v[2:3], v[158:159]
	v_pk_mul_f32 v[0:1], v[0:1], v[156:157]
	v_pk_mul_f32 v[60:61], v[60:61], v[144:145]
	v_pk_mul_f32 v[56:57], v[56:57], v[148:149]
	v_pk_mul_f32 v[52:53], v[52:53], v[152:153]
	v_pk_mul_f32 v[62:63], v[62:63], v[146:147]
	v_pk_mul_f32 v[58:59], v[58:59], v[150:151]
	v_pk_mul_f32 v[54:55], v[54:55], v[154:155]
	v_pk_mul_f32 v[50:51], v[50:51], v[158:159]
	v_pk_mul_f32 v[48:49], v[48:49], v[156:157]
	v_pk_mul_f32 v[44:45], v[44:45], v[144:145]
	v_pk_mul_f32 v[40:41], v[40:41], v[148:149]
	v_pk_mul_f32 v[36:37], v[36:37], v[152:153]
	v_pk_mul_f32 v[46:47], v[46:47], v[146:147]
	v_pk_mul_f32 v[42:43], v[42:43], v[150:151]
	v_pk_mul_f32 v[38:39], v[38:39], v[154:155]
	v_pk_mul_f32 v[34:35], v[34:35], v[158:159]
	v_pk_mul_f32 v[32:33], v[32:33], v[156:157]
	v_pk_mul_f32 v[28:29], v[28:29], v[144:145]
	v_pk_mul_f32 v[24:25], v[24:25], v[148:149]
	v_pk_mul_f32 v[20:21], v[20:21], v[152:153]
	v_pk_mul_f32 v[30:31], v[30:31], v[146:147]
	v_pk_mul_f32 v[26:27], v[26:27], v[150:151]
	v_pk_mul_f32 v[22:23], v[22:23], v[154:155]
	v_pk_mul_f32 v[18:19], v[18:19], v[158:159]
	v_pk_mul_f32 v[16:17], v[16:17], v[156:157]
